# grid barrier steady-state: flat_load/flat_atomic converted to global_* (no aperture check); on v36
# baseline (speedup 1.0000x reference)
.LBB0_329:
	v_readlane_b32 s3, v254, 41
	s_add_u32 s26, s4, s3
	s_addc_u32 s3, s5, 0
	v_mov_b32_e32 v1, s26
	v_add_co_u32_e32 v6, vcc, 0x1000, v1
	v_mov_b32_e32 v1, s3
	s_nop 0
	v_addc_co_u32_e32 v7, vcc, 0, v1, vcc
	global_atomic_add v1, v[6:7], v223, off offset:1024 sc0
	v_cvt_f32_u32_e32 v3, v4
	v_sub_u32_e32 v5, 0, v4
	v_rcp_iflag_f32_e32 v3, v3
	s_nop 0
	v_mul_f32_e32 v3, 0x4f7ffffe, v3
	v_cvt_u32_f32_e32 v3, v3
	v_mul_lo_u32 v5, v5, v3
	v_mul_hi_u32 v5, v3, v5
	v_add_u32_e32 v3, v3, v5
	s_waitcnt vmcnt(0) lgkmcnt(0)
	v_mul_hi_u32 v3, v1, v3
	v_mul_lo_u32 v5, v3, v4
	v_add_u32_e32 v6, 1, v1
	v_sub_u32_e32 v1, v1, v5
	v_add_u32_e32 v7, 1, v3
	v_cmp_ge_u32_e32 vcc, v1, v4
	v_sub_u32_e32 v5, v1, v4
	s_nop 0
	v_cndmask_b32_e32 v3, v3, v7, vcc
	v_cndmask_b32_e32 v1, v1, v5, vcc
	v_add_u32_e32 v5, 1, v3
	v_cmp_ge_u32_e32 vcc, v1, v4
	s_nop 1
	v_cndmask_b32_e32 v1, v3, v5, vcc
	v_mad_u64_u32 v[4:5], s[6:7], v4, v1, v[4:5]
	v_cmp_ne_u32_e32 vcc, v6, v4
	s_and_saveexec_b64 s[6:7], vcc
	s_xor_b64 s[6:7], exec, s[6:7]
	s_cbranch_execz .LBB0_342
	buffer_inv sc1
	v_add_u32_e32 v8, 1, v1
	v_mul_lo_u32 v8, v8, v2
	v_mov_b32_e32 v2, s4
	v_add_co_u32_e32 v2, vcc, 0x3000, v2
	v_mov_b32_e32 v3, s5
	s_nop 0
	v_addc_co_u32_e32 v3, vcc, 0, v3, vcc
	global_load_dword v2, v[2:3], off offset:1024 sc1
	s_add_u32 s10, s4, 0x3400
	s_addc_u32 s11, s5, 0
	s_waitcnt vmcnt(0) lgkmcnt(0)
	v_cmp_lt_u32_e32 vcc, v2, v8
	s_and_saveexec_b64 s[8:9], vcc
	s_cbranch_execz .LBB0_341
	s_mov_b32 s27, 1
	s_mov_b64 s[12:13], 0
	s_branch .LBB0_333

.LBB0_333:
	s_and_b32 s20, s27, 0xff
	s_mov_b64 s[18:19], -1
	s_cmp_lg_u32 s20, 0
	s_mov_b64 s[20:21], -1
	s_sleep 1
	s_cbranch_scc1 .LBB0_337
	v_mov_b64_e32 v[2:3], s[4:5]
	global_load_dword v2, v[2:3], off offset:512 sc1
	s_mov_b64 s[20:21], 0
	s_mov_b64 s[22:23], -1
	s_waitcnt vmcnt(0) lgkmcnt(0)
	v_cmp_eq_u32_e32 vcc, 0, v2
	s_and_saveexec_b64 s[24:25], vcc
	s_cmp_lt_u32 s27, 0x400001
	s_cselect_b64 s[20:21], -1, 0
	s_xor_b64 s[22:23], exec, -1
	s_and_b64 s[20:21], s[20:21], exec
	s_or_b64 exec, exec, s[24:25]
.LBB0_337:
	s_andn2_b64 s[16:17], s[16:17], exec
	s_and_b64 s[22:23], s[22:23], exec
	s_or_b64 s[16:17], s[16:17], s[22:23]
	s_and_saveexec_b64 s[22:23], s[20:21]
	s_cbranch_execz .LBB0_332
	v_mov_b64_e32 v[2:3], s[10:11]
	global_load_dword v2, v[2:3], off sc1
	s_add_i32 s27, s27, 1
	s_or_b64 s[16:17], s[16:17], exec
	s_waitcnt vmcnt(0) lgkmcnt(0)
	v_cmp_ge_u32_e32 vcc, v2, v8
	s_orn2_b64 s[18:19], vcc, exec
	s_branch .LBB0_332
.LBB0_339:
	s_or_b64 exec, exec, s[12:13]
	s_xor_b64 s[10:11], s[14:15], -1
	s_and_saveexec_b64 s[12:13], s[10:11]
	s_xor_b64 s[12:13], exec, s[12:13]
	s_cbranch_execz .LBB0_341
	v_mov_b64_e32 v[2:3], s[4:5]
	global_atomic_add v[2:3], v223, off offset:512

.LBB0_342:
	s_andn2_saveexec_b64 s[6:7], s[6:7]
	s_cbranch_execz .LBB0_358
	v_mov_b32_e32 v1, s4
	v_add_co_u32_e32 v4, vcc, 0x3000, v1
	v_mov_b32_e32 v1, s5
	buffer_wbl2 sc1
	s_waitcnt vmcnt(0)
	v_addc_co_u32_e32 v5, vcc, 0, v1, vcc
	global_atomic_add v1, v[4:5], v223, off offset:1024 sc0
	buffer_inv sc1
	v_cvt_f32_u32_e32 v3, v2
	v_sub_u32_e32 v4, 0, v2
	s_add_u32 s6, s4, 0x3400
	s_addc_u32 s7, s5, 0
	v_rcp_iflag_f32_e32 v3, v3
	s_mov_b64 s[10:11], 0
	v_mul_f32_e32 v3, 0x4f7ffffe, v3
	v_cvt_u32_f32_e32 v3, v3
	v_mul_lo_u32 v4, v4, v3
	v_mul_hi_u32 v4, v3, v4
	v_add_u32_e32 v3, v3, v4
	s_waitcnt vmcnt(0) lgkmcnt(0)
	v_mul_hi_u32 v3, v1, v3
	v_mul_lo_u32 v5, v3, v2
	v_add_u32_e32 v4, 1, v1
	v_sub_u32_e32 v1, v1, v5
	v_add_u32_e32 v6, 1, v3
	v_cmp_ge_u32_e32 vcc, v1, v2
	v_sub_u32_e32 v5, v1, v2
	s_nop 0
	v_cndmask_b32_e32 v3, v3, v6, vcc
	v_cndmask_b32_e32 v1, v1, v5, vcc
	v_add_u32_e32 v5, 1, v3
	v_cmp_ge_u32_e32 vcc, v1, v2
	s_nop 1
	v_cndmask_b32_e32 v1, v3, v5, vcc
	v_mad_u64_u32 v[2:3], s[8:9], v2, v1, v[2:3]
	v_mov_b32_e32 v8, v2
	v_cmp_ne_u32_e32 vcc, v4, v2
	v_mov_b64_e32 v[2:3], s[6:7]
	s_and_saveexec_b64 s[8:9], vcc
	s_cbranch_execz .LBB0_355
	v_mov_b64_e32 v[2:3], s[6:7]
	global_load_dword v2, v[2:3], off sc1
	s_mov_b64 s[14:15], 0
	s_waitcnt vmcnt(0) lgkmcnt(0)
	v_cmp_lt_u32_e32 vcc, v2, v8
	s_and_saveexec_b64 s[12:13], vcc
	s_cbranch_execz .LBB0_354
	s_add_u32 s10, s4, 0x200
	s_addc_u32 s11, s5, 0
	s_mov_b32 s24, 1
	s_mov_b64 s[4:5], 0
	s_branch .LBB0_347

.LBB0_349:
	v_mov_b64_e32 v[2:3], s[10:11]
	global_load_dword v2, v[2:3], off sc1
	s_mov_b64 s[20:21], 0
	s_mov_b64 s[18:19], -1
	s_waitcnt vmcnt(0) lgkmcnt(0)
	v_cmp_eq_u32_e32 vcc, 0, v2
	s_and_saveexec_b64 s[22:23], vcc
	s_cmp_lt_u32 s24, 0x400001
	s_cselect_b64 s[20:21], -1, 0
	s_xor_b64 s[18:19], exec, -1
	s_and_b64 s[20:21], s[20:21], exec
	s_or_b64 exec, exec, s[22:23]
	s_and_saveexec_b64 s[22:23], s[20:21]
	s_cbranch_execz .LBB0_346
.LBB0_352:
	v_mov_b64_e32 v[2:3], s[6:7]
	global_load_dword v2, v[2:3], off sc1
	s_add_i32 s24, s24, 1
	s_or_b64 s[18:19], s[18:19], exec
	s_waitcnt vmcnt(0) lgkmcnt(0)
	v_cmp_ge_u32_e32 vcc, v2, v8
	s_orn2_b64 s[16:17], vcc, exec
	s_branch .LBB0_346

.LBB0_355:
	s_or_b64 exec, exec, s[8:9]
	s_and_saveexec_b64 s[4:5], s[10:11]
	s_cbranch_execz .LBB0_357
	global_atomic_add v[2:3], v223, off
